# weight transposer rewritten (register transpose, no LDS), lru_scan moved to idle waves, last-layer out-proj skips the meta/empty m-tiles (exactly 4 tiles per block)
# speedup vs baseline: 1.4072x; 1.0156x over previous
.LBB0_22:
	s_or_b64 exec, exec, s[2:3]
	s_load_dwordx16 s[84:99], s[0:1], 0x40
	s_load_dwordx4 s[4:7], s[0:1], 0x100
	v_lshlrev_b32_e32 v21, 3, v176
	v_lshlrev_b32_e32 v22, 1, v176
	s_waitcnt lgkmcnt(0)
	v_writelane_b32 v245, s4, 36
	v_writelane_b32 v245, s5, 37
	v_writelane_b32 v245, s6, 38
	v_writelane_b32 v245, s7, 39
	v_readlane_b32 s20, v245, 8
	v_readlane_b32 s21, v245, 9
	v_readfirstlane_b32 s6, v214
	s_nop 0
.Lwt_loop:
	s_cmp_ge_u32 s6, 4032
	s_cbranch_scc1 .Lwt_done
	s_cmp_lt_u32 s6, 2880
	s_cbranch_scc0 .Lwt_r2
	s_cmp_ge_u32 s6, 1440
	s_cselect_b32 s7, 1, 0
	s_mul_i32 s8, s7, 1440
	s_sub_u32 s8, s6, s8
	s_mul_i32 s9, s8, 1457
	s_lshr_b32 s9, s9, 16
	s_mul_i32 s10, s9, 45
	s_sub_u32 s10, s8, s10
	s_movk_i32 s11, 0x1618
	s_mov_b32 s12, 0
	s_mul_i32 s2, s7, 0x1618000
	s_add_u32 s2, s20, s2
	s_addc_u32 s3, s21, 0
	s_mul_i32 s4, s7, 0xb0c000
	s_add_u32 s4, s64, s4
	s_addc_u32 s5, s65, 0
	s_branch .Lwt_common
.Lwt_r2:
	s_cmp_lt_u32 s6, 3904
	s_cbranch_scc0 .Lwt_r3
	s_sub_u32 s8, s6, 2880
	s_lshr_b32 s7, s8, 9
	s_and_b32 s8, s8, 0x1ff
	s_lshr_b32 s9, s8, 3
	s_and_b32 s10, s8, 7
	s_movk_i32 s11, 0x400
	s_mov_b32 s12, 1
	s_lshl_b32 s2, s7, 23
	s_add_u32 s2, s98, s2
	s_addc_u32 s3, s99, 0
	s_lshl_b32 s4, s7, 22
	s_add_u32 s4, s66, s4
	s_addc_u32 s5, s67, 0
	s_branch .Lwt_common
.Lwt_r3:
	s_sub_u32 s8, s6, 3904
	s_lshr_b32 s7, s8, 6
	s_and_b32 s8, s8, 63
	s_lshr_b32 s13, s8, 2
	s_and_b32 s9, s8, 3
	s_mov_b32 s10, 0
	s_movk_i32 s11, 0x80
	s_mov_b32 s12, 2
	s_cmp_eq_u32 s7, 0
	s_cselect_b32 s2, s88, s92
	s_cselect_b32 s3, s89, s93
	s_cselect_b32 s4, s36, s38
	s_cselect_b32 s5, s37, s39
	s_lshl_b32 s14, s13, 16
	s_add_u32 s2, s2, s14
	s_addc_u32 s3, s3, 0
	s_lshl_b32 s14, s13, 15
	s_add_u32 s4, s4, s14
	s_addc_u32 s5, s5, 0
.Lwt_common:
	s_lshl_b32 s15, s11, 2
	s_mul_i32 s14, s9, s15
	s_lshl_b32 s14, s14, 5
	s_lshl_b32 s13, s10, 9
	s_add_u32 s14, s14, s13
	s_add_u32 s2, s2, s14
	s_addc_u32 s3, s3, 0
	s_lshr_b32 s13, s9, s12
	s_mul_i32 s13, s13, s11
	s_add_u32 s14, s12, 6
	s_lshl_b32 s13, s13, s14
	s_lshl_b32 s18, 1, s12
	s_sub_u32 s18, s18, 1
	s_and_b32 s18, s9, s18
	s_lshl_b32 s18, s18, 6
	s_add_u32 s13, s13, s18
	s_add_u32 s4, s4, s13
	s_addc_u32 s5, s5, 0
	s_lshl_b32 s13, s10, 7
	s_lshl_b32 s18, 64, s12
	v_add_u32_e32 v23, s13, v22
	v_cmp_gt_u32_e32 vcc, s11, v23
	v_lshlrev_b32_e32 v24, s14, v23
	v_add_u32_e32 v25, s18, v24
	s_and_saveexec_b64 s[22:23], vcc
	global_load_dwordx2 v[32:33], v21, s[2:3]
	s_add_u32 s2, s2, s15
	s_addc_u32 s3, s3, 0
	global_load_dwordx2 v[34:35], v21, s[2:3]
	s_add_u32 s2, s2, s15
	s_addc_u32 s3, s3, 0
	global_load_dwordx2 v[36:37], v21, s[2:3]
	s_add_u32 s2, s2, s15
	s_addc_u32 s3, s3, 0
	global_load_dwordx2 v[38:39], v21, s[2:3]
	s_add_u32 s2, s2, s15
	s_addc_u32 s3, s3, 0
	global_load_dwordx2 v[40:41], v21, s[2:3]
	s_add_u32 s2, s2, s15
	s_addc_u32 s3, s3, 0
	global_load_dwordx2 v[42:43], v21, s[2:3]
	s_add_u32 s2, s2, s15
	s_addc_u32 s3, s3, 0
	global_load_dwordx2 v[44:45], v21, s[2:3]
	s_add_u32 s2, s2, s15
	s_addc_u32 s3, s3, 0
	global_load_dwordx2 v[46:47], v21, s[2:3]
	s_add_u32 s2, s2, s15
	s_addc_u32 s3, s3, 0
	global_load_dwordx2 v[48:49], v21, s[2:3]
	s_add_u32 s2, s2, s15
	s_addc_u32 s3, s3, 0
	global_load_dwordx2 v[50:51], v21, s[2:3]
	s_add_u32 s2, s2, s15
	s_addc_u32 s3, s3, 0
	global_load_dwordx2 v[52:53], v21, s[2:3]
	s_add_u32 s2, s2, s15
	s_addc_u32 s3, s3, 0
	global_load_dwordx2 v[54:55], v21, s[2:3]
	s_add_u32 s2, s2, s15
	s_addc_u32 s3, s3, 0
	global_load_dwordx2 v[56:57], v21, s[2:3]
	s_add_u32 s2, s2, s15
	s_addc_u32 s3, s3, 0
	global_load_dwordx2 v[58:59], v21, s[2:3]
	s_add_u32 s2, s2, s15
	s_addc_u32 s3, s3, 0
	global_load_dwordx2 v[60:61], v21, s[2:3]
	s_add_u32 s2, s2, s15
	s_addc_u32 s3, s3, 0
	global_load_dwordx2 v[62:63], v21, s[2:3]
	s_add_u32 s2, s2, s15
	s_addc_u32 s3, s3, 0
	global_load_dwordx2 v[64:65], v21, s[2:3]
	s_add_u32 s2, s2, s15
	s_addc_u32 s3, s3, 0
	global_load_dwordx2 v[66:67], v21, s[2:3]
	s_add_u32 s2, s2, s15
	s_addc_u32 s3, s3, 0
	global_load_dwordx2 v[68:69], v21, s[2:3]
	s_add_u32 s2, s2, s15
	s_addc_u32 s3, s3, 0
	global_load_dwordx2 v[70:71], v21, s[2:3]
	s_add_u32 s2, s2, s15
	s_addc_u32 s3, s3, 0
	global_load_dwordx2 v[72:73], v21, s[2:3]
	s_add_u32 s2, s2, s15
	s_addc_u32 s3, s3, 0
	global_load_dwordx2 v[74:75], v21, s[2:3]
	s_add_u32 s2, s2, s15
	s_addc_u32 s3, s3, 0
	global_load_dwordx2 v[76:77], v21, s[2:3]
	s_add_u32 s2, s2, s15
	s_addc_u32 s3, s3, 0
	global_load_dwordx2 v[78:79], v21, s[2:3]
	s_add_u32 s2, s2, s15
	s_addc_u32 s3, s3, 0
	global_load_dwordx2 v[80:81], v21, s[2:3]
	s_add_u32 s2, s2, s15
	s_addc_u32 s3, s3, 0
	global_load_dwordx2 v[82:83], v21, s[2:3]
	s_add_u32 s2, s2, s15
	s_addc_u32 s3, s3, 0
	global_load_dwordx2 v[84:85], v21, s[2:3]
	s_add_u32 s2, s2, s15
	s_addc_u32 s3, s3, 0
	global_load_dwordx2 v[86:87], v21, s[2:3]
	s_add_u32 s2, s2, s15
	s_addc_u32 s3, s3, 0
	global_load_dwordx2 v[88:89], v21, s[2:3]
	s_add_u32 s2, s2, s15
	s_addc_u32 s3, s3, 0
	global_load_dwordx2 v[90:91], v21, s[2:3]
	s_add_u32 s2, s2, s15
	s_addc_u32 s3, s3, 0
	global_load_dwordx2 v[92:93], v21, s[2:3]
	s_add_u32 s2, s2, s15
	s_addc_u32 s3, s3, 0
	global_load_dwordx2 v[94:95], v21, s[2:3]
	s_waitcnt vmcnt(30)
	v_cvt_pk_bf16_f32 v96, v32, v34
	v_cvt_pk_bf16_f32 v112, v33, v35
	s_waitcnt vmcnt(28)
	v_cvt_pk_bf16_f32 v97, v36, v38
	v_cvt_pk_bf16_f32 v113, v37, v39
	s_waitcnt vmcnt(26)
	v_cvt_pk_bf16_f32 v98, v40, v42
	v_cvt_pk_bf16_f32 v114, v41, v43
	s_waitcnt vmcnt(24)
	v_cvt_pk_bf16_f32 v99, v44, v46
	v_cvt_pk_bf16_f32 v115, v45, v47
	s_waitcnt vmcnt(22)
	v_cvt_pk_bf16_f32 v100, v48, v50
	v_cvt_pk_bf16_f32 v116, v49, v51
	s_waitcnt vmcnt(20)
	v_cvt_pk_bf16_f32 v101, v52, v54
	v_cvt_pk_bf16_f32 v117, v53, v55
	s_waitcnt vmcnt(18)
	v_cvt_pk_bf16_f32 v102, v56, v58
	v_cvt_pk_bf16_f32 v118, v57, v59
	s_waitcnt vmcnt(16)
	v_cvt_pk_bf16_f32 v103, v60, v62
	v_cvt_pk_bf16_f32 v119, v61, v63
	s_waitcnt vmcnt(14)
	v_cvt_pk_bf16_f32 v104, v64, v66
	v_cvt_pk_bf16_f32 v120, v65, v67
	s_waitcnt vmcnt(12)
	v_cvt_pk_bf16_f32 v105, v68, v70
	v_cvt_pk_bf16_f32 v121, v69, v71
	s_waitcnt vmcnt(10)
	v_cvt_pk_bf16_f32 v106, v72, v74
	v_cvt_pk_bf16_f32 v122, v73, v75
	s_waitcnt vmcnt(8)
	v_cvt_pk_bf16_f32 v107, v76, v78
	v_cvt_pk_bf16_f32 v123, v77, v79
	s_waitcnt vmcnt(6)
	v_cvt_pk_bf16_f32 v108, v80, v82
	v_cvt_pk_bf16_f32 v124, v81, v83
	s_waitcnt vmcnt(4)
	v_cvt_pk_bf16_f32 v109, v84, v86
	v_cvt_pk_bf16_f32 v125, v85, v87
	s_waitcnt vmcnt(2)
	v_cvt_pk_bf16_f32 v110, v88, v90
	v_cvt_pk_bf16_f32 v126, v89, v91
	s_waitcnt vmcnt(0)
	v_cvt_pk_bf16_f32 v111, v92, v94
	v_cvt_pk_bf16_f32 v127, v93, v95
	global_store_dwordx4 v24, v[96:99], s[4:5] offset:0
	global_store_dwordx4 v24, v[100:103], s[4:5] offset:16
	global_store_dwordx4 v24, v[104:107], s[4:5] offset:32
	global_store_dwordx4 v24, v[108:111], s[4:5] offset:48
	global_store_dwordx4 v25, v[112:115], s[4:5] offset:0
	global_store_dwordx4 v25, v[116:119], s[4:5] offset:16
	global_store_dwordx4 v25, v[120:123], s[4:5] offset:32
	global_store_dwordx4 v25, v[124:127], s[4:5] offset:48
	s_or_b64 exec, exec, s[22:23]
	s_add_u32 s6, s6, s33
	s_branch .Lwt_loop
.Lwt_done:
	s_waitcnt vmcnt(0)
.LBB0_78:
	v_lshrrev_b32_e32 v2, 20, v0
	v_lshrrev_b32_e32 v0, 10, v0
	v_or_b32_e32 v0, v0, v2
	s_movk_i32 s0, 0x3ff
	v_and_or_b32 v0, v0, s0, v177
	v_cmp_eq_u32_e32 vcc, 0, v0
	s_barrier
	s_and_saveexec_b64 s[0:1], vcc
	s_cbranch_execz .LBB0_88
	v_readlane_b32 s2, v245, 0
	v_readlane_b32 s3, v245, 1
	buffer_wbl2 sc1
	s_waitcnt vmcnt(0)
	s_load_dwordx2 s[2:3], s[2:3], 0x58
	v_mov_b32_e32 v3, 0
	s_mov_b64 s[4:5], exec
	v_mbcnt_lo_u32_b32 v2, s4, 0
	v_mbcnt_hi_u32_b32 v2, s5, v2
	s_waitcnt lgkmcnt(0)
	global_load_dword v0, v3, s[2:3] offset:40
	v_cmp_eq_u32_e32 vcc, 0, v2
	s_and_saveexec_b64 s[6:7], vcc
	s_cbranch_execz .LBB0_81
	s_bcnt1_i32_b64 s4, s[4:5]
	v_mov_b32_e32 v4, s4
	global_atomic_add v4, v3, v4, s[2:3] offset:32 sc0

.LBB0_224:
	s_or_b64 exec, exec, s[0:1]
	v_add_u32_e32 v28, 0xffff0000, v28
	v_cmp_gt_u32_e32 vcc, s38, v28
	s_and_saveexec_b64 s[0:1], vcc
	s_cbranch_execz .LBB0_229
	v_add_u16_e32 v16, s7, v177
	s_mov_b64 s[2:3], 0

.LBB0_354:
	s_or_b64 exec, exec, s[0:1]
	v_readlane_b32 s2, v245, 47
	v_mov_b32_e32 v0, v177
	v_readlane_b32 s3, v245, 48
	s_barrier
	s_andn2_b64 vcc, exec, s[2:3]
	v_readfirstlane_b32 s0, v0
	s_barrier
	s_cbranch_vccnz .LBB0_369
	s_ashr_i32 s6, s0, 7
	s_ashr_i32 s2, s0, 6
	s_lshl_b32 s0, s6, 13
	s_add_i32 s7, s0, 0x4000
	v_readlane_b32 s0, v245, 61
	s_and_b32 s3, s2, 1
	v_bfe_u32 v150, v0, 3, 3
	s_lshl_b32 s0, s0, 22
	s_add_u32 s0, s66, s0
	v_bitop3_b32 v1, v150, v0, 7 bitop3:0x78
	v_readlane_b32 s25, v245, 54
	s_addc_u32 s1, s67, 0
	v_readlane_b32 s29, v245, 61
	s_nop 1
	s_cmp_lg_u32 s29, 0
	s_cselect_b32 s89, 0x100, s89
	s_cselect_b32 s28, 0x400, 0
	s_cmp_eq_u32 s31, 0
	s_cselect_b32 s28, s28, 0
	s_add_u32 s25, s25, s28
	s_lshl_b32 s8, s2, 5
	v_or_b32_e32 v4, s25, v150
	v_lshlrev_b32_e32 v178, 4, v1
	v_readlane_b32 s26, v245, 55
	v_lshl_add_u64 v[128:129], s[56:57], 0, v[178:179]
	v_add_u32_e32 v2, s8, v4
	v_or_b32_e32 v1, s26, v150
	v_lshl_add_u64 v[130:131], s[0:1], 0, v[178:179]
	v_mad_i64_i32 v[132:133], s[0:1], v2, s13, v[128:129]
	v_add_u32_e32 v2, s8, v1
	v_ashrrev_i32_e32 v3, 31, v2
	v_lshlrev_b64 v[2:3], 7, v[2:3]
	s_or_b32 s9, s8, 8
	v_lshl_add_u64 v[64:65], v[130:131], 0, v[2:3]
	v_add_u32_e32 v2, s9, v4
	v_mad_i64_i32 v[134:135], s[0:1], v2, s13, v[128:129]
	v_add_u32_e32 v2, s9, v1
	v_ashrrev_i32_e32 v3, 31, v2
	v_lshlrev_b64 v[2:3], 7, v[2:3]
	s_or_b32 s10, s8, 16
	v_lshl_add_u64 v[66:67], v[130:131], 0, v[2:3]
	v_add_u32_e32 v2, s10, v4
	v_mad_i64_i32 v[136:137], s[0:1], v2, s13, v[128:129]
	v_add_u32_e32 v2, s10, v1
	s_lshl_b32 s16, s2, 12
	v_ashrrev_i32_e32 v3, 31, v2
	s_mov_b32 m0, s16
	v_lshlrev_b64 v[2:3], 7, v[2:3]
	s_or_b32 s11, s8, 24
	global_load_lds_dwordx4 v[132:133], off
	s_or_b32 m0, s16, 0x400
	v_lshl_add_u64 v[68:69], v[130:131], 0, v[2:3]
	v_add_u32_e32 v2, s11, v4
	global_load_lds_dwordx4 v[134:135], off
	s_or_b32 m0, s16, 0x800
	v_mad_i64_i32 v[140:141], s[0:1], v2, s13, v[128:129]
	global_load_lds_dwordx4 v[136:137], off
	s_or_b32 m0, s16, 0xc00
	s_add_i32 s18, s16, 0x4000
	v_add_u32_e32 v2, s11, v1
	global_load_lds_dwordx4 v[140:141], off
	s_mov_b32 m0, s18
	s_add_i32 s19, s16, 0x4400
	v_ashrrev_i32_e32 v3, 31, v2
	global_load_lds_dwordx4 v[64:65], off
	s_mov_b32 m0, s19
	s_add_i32 s22, s16, 0x4800
	v_lshlrev_b64 v[2:3], 7, v[2:3]
	global_load_lds_dwordx4 v[66:67], off
	s_mov_b32 m0, s22
	s_add_i32 s23, s16, 0x4c00
	v_lshl_add_u64 v[70:71], v[130:131], 0, v[2:3]
	global_load_lds_dwordx4 v[68:69], off
	s_mov_b32 m0, s23
	v_and_b32_e32 v1, 31, v0
	global_load_lds_dwordx4 v[70:71], off
	v_bfe_u32 v2, v0, 5, 1
	v_and_b32_e32 v3, 7, v0
	v_lshlrev_b32_e32 v4, 7, v1
	v_bitop3_b32 v0, v2, v0, 7 bitop3:0x78
	v_lshl_or_b32 v5, s3, 13, v4
	v_or_b32_e32 v4, s7, v4
	v_lshlrev_b32_e32 v0, 4, v0
	v_or_b32_e32 v151, v5, v0
	v_or_b32_e32 v152, v4, v0
	v_bitop3_b32 v0, v2, v3, 2 bitop3:0x36
	v_lshlrev_b32_e32 v0, 4, v0
	v_or_b32_e32 v153, v5, v0
	v_or_b32_e32 v154, v0, v4
	v_bitop3_b32 v0, v2, v3, 4 bitop3:0x36
	v_lshlrev_b32_e32 v0, 4, v0
	v_or_b32_e32 v155, v5, v0
	v_or_b32_e32 v156, v0, v4
	v_bitop3_b32 v0, v2, v3, 6 bitop3:0x36
	v_lshlrev_b32_e32 v0, 4, v0
	v_or_b32_e32 v157, v5, v0
	v_or_b32_e32 v158, v0, v4
	s_mul_i32 s0, s2, 0x1200
	v_lshlrev_b32_e32 v0, 3, v3
	v_lshl_or_b32 v159, s6, 6, v0
	v_mov_b32_e32 v0, s0
	v_mad_u32_u24 v0, v1, s12, v0
	v_lshlrev_b32_e32 v1, 3, v2
	v_lshlrev_b32_e32 v2, 4, v3
	v_or_b32_e32 v3, s0, v2
	v_mul_u32_u24_e32 v4, 0x90, v150
	v_and_b32_e32 v178, 48, v2
	v_lshl_or_b32 v160, s3, 6, v150
	v_lshl_add_u64 v[138:139], s[58:59], 0, v[178:179]
	v_add_u32_e32 v161, v0, v1
	v_add_u32_e32 v162, v3, v4
	v_readlane_b32 s24, v245, 51
	s_branch .LBB0_358
.LBB0_356:
	s_min_u32 s6, s24, 0x100
	s_and_b32 s2, s24, 63
	s_add_i32 s3, s24, 0xffffff00
	s_and_b32 s6, s6, 0x1c0
	s_cmpk_gt_u32 s24, 0xff
	v_readlane_b32 s7, v245, 50
	s_cselect_b32 s7, s7, 8
	s_cselect_b32 s2, s3, s2
	v_cvt_f32_ubyte0_e32 v64, s7
	v_rcp_iflag_f32_e32 v64, v64
	s_sub_i32 s28, 0, s7
	s_abs_i32 s27, s2
	s_ashr_i32 s3, s2, 31
	v_mul_f32_e32 v64, 0x4f7ffffe, v64
	v_cvt_u32_f32_e32 v64, v64
	s_mov_b32 m0, s16
	v_readfirstlane_b32 s29, v64
	s_mul_i32 s28, s28, s29
	s_mul_hi_u32 s28, s29, s28
	s_add_i32 s29, s29, s28
	s_mul_hi_u32 s28, s27, s29
	s_mul_i32 s29, s28, s7
	s_sub_i32 s27, s27, s29
	s_add_i32 s29, s28, 1
	s_sub_i32 s30, s27, s7
	s_cmp_ge_u32 s27, s7
	s_cselect_b32 s28, s29, s28
	s_cselect_b32 s27, s30, s27
	s_add_i32 s29, s28, 1
	s_cmp_ge_u32 s27, s7
	s_cselect_b32 s27, s29, s28
	s_xor_b32 s27, s27, s3
	s_sub_i32 s27, s27, s3
	s_mul_i32 s3, s27, s7
	s_sub_i32 s2, s2, s3
	s_lshl_b32 s2, s2, 3
	s_add_i32 s2, s2, s6
	s_or_b32 s2, s2, s31
	v_readlane_b32 s29, v245, 61
	s_lshr_b32 s28, s2, 3
	s_lshl_b32 s30, s31, 3
	s_cmp_ge_u32 s28, s30
	s_cselect_b32 s28, 8, 0
	s_cmp_lt_u32 s31, 4
	s_cselect_b32 s28, s28, 0
	s_cmp_lg_u32 s29, 0
	s_cselect_b32 s28, s28, 0
	s_add_u32 s2, s2, s28
	s_lshl_b32 s3, s2, 7
	v_or_b32_e32 v70, s3, v150
	s_lshl_b32 s2, s27, 7
	v_add_u32_e32 v64, s8, v70
	v_or_b32_e32 v71, s2, v150
	v_mad_i64_i32 v[132:133], s[6:7], v64, s13, v[128:129]
	v_add_u32_e32 v66, s9, v70
	v_add_u32_e32 v64, s8, v71
	v_mad_i64_i32 v[134:135], s[6:7], v66, s13, v[128:129]
	v_add_u32_e32 v68, s10, v70
	global_load_lds_dwordx4 v[132:133], off
	s_add_i32 m0, s16, 0x400
	v_ashrrev_i32_e32 v65, 31, v64
	v_add_u32_e32 v66, s9, v71
	v_mad_i64_i32 v[136:137], s[6:7], v68, s13, v[128:129]
	v_add_u32_e32 v70, s11, v70
	global_load_lds_dwordx4 v[134:135], off
	s_add_i32 m0, s16, 0x800
	v_lshlrev_b64 v[64:65], 7, v[64:65]
	v_ashrrev_i32_e32 v67, 31, v66
	v_add_u32_e32 v68, s10, v71
	v_mad_i64_i32 v[140:141], s[6:7], v70, s13, v[128:129]
	global_load_lds_dwordx4 v[136:137], off
	s_add_i32 m0, s16, 0xc00
	v_lshl_add_u64 v[64:65], v[130:131], 0, v[64:65]
	v_lshlrev_b64 v[66:67], 7, v[66:67]
	v_ashrrev_i32_e32 v69, 31, v68
	v_add_u32_e32 v70, s11, v71
	global_load_lds_dwordx4 v[140:141], off
	s_mov_b32 m0, s18
	v_lshl_add_u64 v[66:67], v[130:131], 0, v[66:67]
	v_lshlrev_b64 v[68:69], 7, v[68:69]
	v_ashrrev_i32_e32 v71, 31, v70
	global_load_lds_dwordx4 v[64:65], off
	s_mov_b32 m0, s19
	v_lshl_add_u64 v[68:69], v[130:131], 0, v[68:69]
	v_lshlrev_b64 v[70:71], 7, v[70:71]
	global_load_lds_dwordx4 v[66:67], off
	s_mov_b32 m0, s22
	v_lshl_add_u64 v[70:71], v[130:131], 0, v[70:71]
	global_load_lds_dwordx4 v[68:69], off
	s_mov_b32 m0, s23
	s_nop 0
	global_load_lds_dwordx4 v[70:71], off
